# v43 with the ssm_a WA ring 15 k-steps deep (30 loads issued up front) instead of 12
# speedup vs baseline: 1.0069x; 1.0045x over previous
; #define LAS __attribute__((address_space(3)))
; __device__ __forceinline__ void ssm_stage_u(unsigned char* ws, LAS unsigned char* lds, int g, int cb, int hh, int tid) {
;     ...
;     for (int r = 0; r < 8; ++r) { const int c = r * 512 + tid, jj = c >> 7, col = (c >> 1) & 63, part = c & 1;
;         v[r] = *(const u32x4*)(U + ((size_t)((cb * 64 + col) * 64 + hh * 32 + jj) * 512 + g * 16 + part * 8)); }
; #pragma unroll
;     for (int r = 0; r < 8; ++r) { const int c = r * 512 + tid; *(LAS u32x4*)(lds + SS_UB + c * 16) = v[r]; }
; __device__ __forceinline__ void ssm_a_task(unsigned char* ws, LAS unsigned char* lds, int task, int tid) {
;     ...
;     const bf16* WA = (const bf16*)(ws + WS_WA) + ((size_t)(g * 256 + wid * 32 + rr) * 1024 + 8 * kk);
;     for (int hh = 0; hh < 2; ++hh) {
;         ssm_stage_u(ws, lds, g, cb, hh, tid);
;         __syncthreads();
; #pragma unroll 4
;         for (int ks = 0; ks < 16; ++ks) {
;             bf16x8 bfr[4], afr[2];
; #pragma unroll
;             for (int a = 0; a < 2; ++a) afr[a] = *(const bf16x8*)(WA + (size_t)a * 16 * 1024 + (hh * 16 + ks) * 32);
.LBB0_603:
	s_ashr_i32 s16, s54, 3
	v_mov_b32_e32 v30, v44
	s_and_b32 s17, s54, 7
	s_lshl_b32 s14, s16, 4
	s_lshl_b32 s3, s17, 12
	v_lshlrev_b32_e32 v0, 5, v30
	s_ashr_i32 s15, s14, 31
	v_and_b32_e32 v0, 0xfc0, v0
	s_lshl_b64 s[14:15], s[14:15], 1
	v_or_b32_e32 v31, s3, v0
	v_ashrrev_i32_e32 v0, 7, v30
	v_add_u32_e32 v4, 0x200, v30
	s_add_u32 s34, s4, s14
	s_waitcnt vmcnt(1)
	v_lshlrev_b32_e32 v38, 4, v30
	v_add_u32_e32 v0, v31, v0
	v_ashrrev_i32_e32 v4, 7, v4
	v_add_u32_e32 v8, 0x400, v30
	s_addc_u32 s35, s5, s15
	v_and_b32_e32 v184, 16, v38
	v_ashrrev_i32_e32 v1, 31, v0
	v_add_u32_e32 v4, v31, v4
	v_ashrrev_i32_e32 v8, 7, v8
	v_add_u32_e32 v12, 0x600, v30
	v_lshl_add_u64 v[28:29], s[34:35], 0, v[184:185]
	v_lshlrev_b64 v[0:1], 10, v[0:1]
	v_ashrrev_i32_e32 v5, 31, v4
	v_add_u32_e32 v8, v31, v8
	v_ashrrev_i32_e32 v12, 7, v12
	v_add_u32_e32 v16, 0x800, v30
	v_lshl_add_u64 v[0:1], v[28:29], 0, v[0:1]
	v_lshlrev_b64 v[4:5], 10, v[4:5]
	v_ashrrev_i32_e32 v9, 31, v8
	v_add_u32_e32 v12, v31, v12
	v_ashrrev_i32_e32 v16, 7, v16
	v_add_u32_e32 v20, 0xa00, v30
	global_load_dwordx4 v[0:3], v[0:1], off
	v_lshl_add_u64 v[4:5], v[28:29], 0, v[4:5]
	v_lshlrev_b64 v[8:9], 10, v[8:9]
	v_ashrrev_i32_e32 v13, 31, v12
	v_add_u32_e32 v16, v31, v16
	v_ashrrev_i32_e32 v20, 7, v20
	v_add_u32_e32 v24, 0xc00, v30
	global_load_dwordx4 v[4:7], v[4:5], off
	v_lshl_add_u64 v[8:9], v[28:29], 0, v[8:9]
	v_lshlrev_b64 v[12:13], 10, v[12:13]
	v_ashrrev_i32_e32 v17, 31, v16
	v_add_u32_e32 v20, v31, v20
	v_ashrrev_i32_e32 v24, 7, v24
	v_add_u32_e32 v30, 0xe00, v30
	global_load_dwordx4 v[8:11], v[8:9], off
	v_lshl_add_u64 v[12:13], v[28:29], 0, v[12:13]
	v_lshlrev_b64 v[16:17], 10, v[16:17]
	v_ashrrev_i32_e32 v21, 31, v20
	v_add_u32_e32 v24, v31, v24
	v_ashrrev_i32_e32 v30, 7, v30
	global_load_dwordx4 v[12:15], v[12:13], off
	v_lshl_add_u64 v[16:17], v[28:29], 0, v[16:17]
	v_lshlrev_b64 v[20:21], 10, v[20:21]
	v_ashrrev_i32_e32 v25, 31, v24
	v_add_u32_e32 v30, v31, v30
	global_load_dwordx4 v[16:19], v[16:17], off
	v_lshl_add_u64 v[20:21], v[28:29], 0, v[20:21]
	v_lshlrev_b64 v[24:25], 10, v[24:25]
	v_ashrrev_i32_e32 v31, 31, v30
	global_load_dwordx4 v[20:23], v[20:21], off
	v_lshl_add_u64 v[24:25], v[28:29], 0, v[24:25]
	v_lshlrev_b64 v[30:31], 10, v[30:31]
	global_load_dwordx4 v[24:27], v[24:25], off
	v_lshl_add_u64 v[28:29], v[28:29], 0, v[30:31]
	global_load_dwordx4 v[28:31], v[28:29], off
	v_add_u32_e32 v38, 0, v38
	v_add_u32_e32 v38, 0x10000, v38
	s_mov_b32 s12, 0
	v_lshl_add_u32 v132, s16, 8, v46
	v_ashrrev_i32_e32 v133, 31, v132
	v_lshlrev_b64 v[132:133], 11, v[132:133]
	v_lshl_add_u64 v[40:41], v[34:35], 0, v[132:133]
	v_add_co_u32_e32 v164, vcc, 0xffff8000, v40
	s_nop 1
	v_addc_co_u32_e32 v165, vcc, -1, v41, vcc
	global_load_dwordx4 v[80:83], v[40:41], off offset:-192
	global_load_dwordx4 v[84:87], v[164:165], off offset:-192
	global_load_dwordx4 v[88:91], v[40:41], off offset:-128
	global_load_dwordx4 v[92:95], v[164:165], off offset:-128
	global_load_dwordx4 v[96:99], v[40:41], off offset:-64
	global_load_dwordx4 v[100:103], v[164:165], off offset:-64
	global_load_dwordx4 v[104:107], v[40:41], off offset:0
	global_load_dwordx4 v[108:111], v[164:165], off offset:0
	global_load_dwordx4 v[112:115], v[40:41], off offset:64
	global_load_dwordx4 v[116:119], v[164:165], off offset:64
	global_load_dwordx4 v[120:123], v[40:41], off offset:128
	global_load_dwordx4 v[124:127], v[164:165], off offset:128
	global_load_dwordx4 v[128:131], v[40:41], off offset:192
	global_load_dwordx4 v[168:171], v[164:165], off offset:192
	global_load_dwordx4 v[172:175], v[40:41], off offset:256
	global_load_dwordx4 v[176:179], v[164:165], off offset:256
	global_load_dwordx4 v[180:183], v[40:41], off offset:320
	global_load_dwordx4 v[186:189], v[164:165], off offset:320
	global_load_dwordx4 v[190:193], v[40:41], off offset:384
	global_load_dwordx4 v[194:197], v[164:165], off offset:384
	global_load_dwordx4 v[198:201], v[40:41], off offset:448
	global_load_dwordx4 v[202:205], v[164:165], off offset:448
	global_load_dwordx4 v[206:209], v[40:41], off offset:512
	global_load_dwordx4 v[210:213], v[164:165], off offset:512
	global_load_dwordx4 v[224:227], v[40:41], off offset:576
	global_load_dwordx4 v[228:231], v[164:165], off offset:576
	global_load_dwordx4 v[232:235], v[40:41], off offset:640
	global_load_dwordx4 v[236:239], v[164:165], off offset:640
	global_load_dwordx4 v[240:243], v[40:41], off offset:704
	global_load_dwordx4 v[244:247], v[164:165], off offset:704
	s_waitcnt vmcnt(37)
	ds_write_b128 v38, v[0:3]
	s_waitcnt vmcnt(36)
	ds_write_b128 v38, v[4:7] offset:8192
	s_waitcnt vmcnt(35)
	ds_write_b128 v38, v[8:11] offset:16384
	s_waitcnt vmcnt(34)
	ds_write_b128 v38, v[12:15] offset:24576
	s_waitcnt vmcnt(33)
	ds_write_b128 v38, v[16:19] offset:32768
	s_waitcnt vmcnt(32)
	ds_write_b128 v38, v[20:23] offset:40960
	s_waitcnt vmcnt(31)
	ds_write_b128 v38, v[24:27] offset:49152
	s_waitcnt vmcnt(30)
	ds_write_b128 v38, v[28:31] offset:57344
	v_lshl_add_u32 v0, s16, 8, v46
	v_ashrrev_i32_e32 v1, 31, v0
	v_lshlrev_b64 v[38:39], 11, v[0:1]
	v_mov_b32_e32 v0, 0
	v_lshl_add_u64 v[40:41], v[34:35], 0, v[38:39]
	v_mov_b32_e32 v1, v0
	v_mov_b32_e32 v2, v0
	v_mov_b32_e32 v3, v0
	v_mov_b32_e32 v4, v0
	v_mov_b32_e32 v5, v0
	v_mov_b32_e32 v6, v0
	v_mov_b32_e32 v7, v0
	v_mov_b32_e32 v8, v0
	v_mov_b32_e32 v9, v0
	v_mov_b32_e32 v10, v0
	v_mov_b32_e32 v11, v0
	v_mov_b32_e32 v12, v0
	v_mov_b32_e32 v13, v0
	v_mov_b32_e32 v14, v0
	v_mov_b32_e32 v15, v0
	v_mov_b32_e32 v16, v0
	v_mov_b32_e32 v17, v0
	v_mov_b32_e32 v18, v0
	v_mov_b32_e32 v19, v0
	v_mov_b32_e32 v20, v0
	v_mov_b32_e32 v21, v0
	v_mov_b32_e32 v22, v0
	v_mov_b32_e32 v23, v0
	v_mov_b32_e32 v24, v0
	v_mov_b32_e32 v25, v0
	v_mov_b32_e32 v26, v0
	v_mov_b32_e32 v27, v0
	v_mov_b32_e32 v28, v0
	v_mov_b32_e32 v29, v0
	v_mov_b32_e32 v30, v0
	v_mov_b32_e32 v31, v0
	s_waitcnt lgkmcnt(0)
	s_barrier
; #define LAS __attribute__((address_space(3)))
; __device__ __forceinline__ void ssm_a_task(unsigned char* ws, LAS unsigned char* lds, int task, int tid) {
;     ...
;         for (int ks = 0; ks < 16; ++ks) {
;             bf16x8 bfr[4], afr[2];
; #pragma unroll
;             for (int a = 0; a < 2; ++a) afr[a] = *(const bf16x8*)(WA + (size_t)a * 16 * 1024 + (hh * 16 + ks) * 32);
; #pragma unroll
;             for (int c = 0; c < 4; ++c) bfr[c] = *(const LAS bf16x8*)(lds + SS_UB + (((2 * ks + (kk >> 1)) * 64 + c * 16 + rr) * 32 + (kk & 1) * 16));
; #pragma unroll
;             for (int a = 0; a < 2; ++a)
; #pragma unroll
;                 for (int c = 0; c < 4; ++c) acc[a][c] = __builtin_amdgcn_mfma_f32_16x16x32_bf16(afr[a], bfr[c], acc[a][c], 0, 0, 0);
;         }
.LBB0_604:
	v_add_u32_e32 v166, 0x10000, v47
	ds_read_b128 v[132:135], v166 offset:0
	ds_read_b128 v[136:139], v166 offset:512
	ds_read_b128 v[140:143], v166 offset:1024
	ds_read_b128 v[144:147], v166 offset:1536
	ds_read_b128 v[148:151], v166 offset:4096
	ds_read_b128 v[152:155], v166 offset:4608
	ds_read_b128 v[156:159], v166 offset:5120
	ds_read_b128 v[160:163], v166 offset:5632
	s_waitcnt lgkmcnt(4)
	s_waitcnt vmcnt(29)
	v_mfma_f32_16x16x32_bf16 v[12:15], v[80:83], v[132:135], v[12:15]
	v_mfma_f32_16x16x32_bf16 v[8:11], v[80:83], v[136:139], v[8:11]
	v_mfma_f32_16x16x32_bf16 v[4:7], v[80:83], v[140:143], v[4:7]
	v_mfma_f32_16x16x32_bf16 v[0:3], v[80:83], v[144:147], v[0:3]
	s_waitcnt vmcnt(28)
	v_mfma_f32_16x16x32_bf16 v[28:31], v[84:87], v[132:135], v[28:31]
	v_mfma_f32_16x16x32_bf16 v[24:27], v[84:87], v[136:139], v[24:27]
	v_mfma_f32_16x16x32_bf16 v[20:23], v[84:87], v[140:143], v[20:23]
	v_mfma_f32_16x16x32_bf16 v[16:19], v[84:87], v[144:147], v[16:19]
	global_load_dwordx4 v[80:83], v[40:41], off offset:768
	global_load_dwordx4 v[84:87], v[164:165], off offset:768
	ds_read_b128 v[132:135], v166 offset:8192
	ds_read_b128 v[136:139], v166 offset:8704
	ds_read_b128 v[140:143], v166 offset:9216
	ds_read_b128 v[144:147], v166 offset:9728
	s_waitcnt lgkmcnt(4)
	s_waitcnt vmcnt(29)
	v_mfma_f32_16x16x32_bf16 v[12:15], v[88:91], v[148:151], v[12:15]
	v_mfma_f32_16x16x32_bf16 v[8:11], v[88:91], v[152:155], v[8:11]
	v_mfma_f32_16x16x32_bf16 v[4:7], v[88:91], v[156:159], v[4:7]
	v_mfma_f32_16x16x32_bf16 v[0:3], v[88:91], v[160:163], v[0:3]
	s_waitcnt vmcnt(28)
	v_mfma_f32_16x16x32_bf16 v[28:31], v[92:95], v[148:151], v[28:31]
	v_mfma_f32_16x16x32_bf16 v[24:27], v[92:95], v[152:155], v[24:27]
	v_mfma_f32_16x16x32_bf16 v[20:23], v[92:95], v[156:159], v[20:23]
	v_mfma_f32_16x16x32_bf16 v[16:19], v[92:95], v[160:163], v[16:19]
	ds_read_b128 v[148:151], v166 offset:12288
	ds_read_b128 v[152:155], v166 offset:12800
	ds_read_b128 v[156:159], v166 offset:13312
	ds_read_b128 v[160:163], v166 offset:13824
	s_waitcnt lgkmcnt(4)
	s_waitcnt vmcnt(27)
	v_mfma_f32_16x16x32_bf16 v[12:15], v[96:99], v[132:135], v[12:15]
	v_mfma_f32_16x16x32_bf16 v[8:11], v[96:99], v[136:139], v[8:11]
	v_mfma_f32_16x16x32_bf16 v[4:7], v[96:99], v[140:143], v[4:7]
	v_mfma_f32_16x16x32_bf16 v[0:3], v[96:99], v[144:147], v[0:3]
	s_waitcnt vmcnt(26)
	v_mfma_f32_16x16x32_bf16 v[28:31], v[100:103], v[132:135], v[28:31]
	v_mfma_f32_16x16x32_bf16 v[24:27], v[100:103], v[136:139], v[24:27]
	v_mfma_f32_16x16x32_bf16 v[20:23], v[100:103], v[140:143], v[20:23]
	v_mfma_f32_16x16x32_bf16 v[16:19], v[100:103], v[144:147], v[16:19]
	ds_read_b128 v[132:135], v166 offset:16384
	ds_read_b128 v[136:139], v166 offset:16896
	ds_read_b128 v[140:143], v166 offset:17408
	ds_read_b128 v[144:147], v166 offset:17920
	s_waitcnt lgkmcnt(4)
	s_waitcnt vmcnt(25)
	v_mfma_f32_16x16x32_bf16 v[12:15], v[104:107], v[148:151], v[12:15]
	v_mfma_f32_16x16x32_bf16 v[8:11], v[104:107], v[152:155], v[8:11]
	v_mfma_f32_16x16x32_bf16 v[4:7], v[104:107], v[156:159], v[4:7]
	v_mfma_f32_16x16x32_bf16 v[0:3], v[104:107], v[160:163], v[0:3]
	s_waitcnt vmcnt(24)
	v_mfma_f32_16x16x32_bf16 v[28:31], v[108:111], v[148:151], v[28:31]
	v_mfma_f32_16x16x32_bf16 v[24:27], v[108:111], v[152:155], v[24:27]
	v_mfma_f32_16x16x32_bf16 v[20:23], v[108:111], v[156:159], v[20:23]
	v_mfma_f32_16x16x32_bf16 v[16:19], v[108:111], v[160:163], v[16:19]
	ds_read_b128 v[148:151], v166 offset:20480
	ds_read_b128 v[152:155], v166 offset:20992
	ds_read_b128 v[156:159], v166 offset:21504
	ds_read_b128 v[160:163], v166 offset:22016
	s_waitcnt lgkmcnt(4)
	s_waitcnt vmcnt(23)
	v_mfma_f32_16x16x32_bf16 v[12:15], v[112:115], v[132:135], v[12:15]
	v_mfma_f32_16x16x32_bf16 v[8:11], v[112:115], v[136:139], v[8:11]
	v_mfma_f32_16x16x32_bf16 v[4:7], v[112:115], v[140:143], v[4:7]
	v_mfma_f32_16x16x32_bf16 v[0:3], v[112:115], v[144:147], v[0:3]
	s_waitcnt vmcnt(22)
	v_mfma_f32_16x16x32_bf16 v[28:31], v[116:119], v[132:135], v[28:31]
	v_mfma_f32_16x16x32_bf16 v[24:27], v[116:119], v[136:139], v[24:27]
	v_mfma_f32_16x16x32_bf16 v[20:23], v[116:119], v[140:143], v[20:23]
	v_mfma_f32_16x16x32_bf16 v[16:19], v[116:119], v[144:147], v[16:19]
	ds_read_b128 v[132:135], v166 offset:24576
	ds_read_b128 v[136:139], v166 offset:25088
	ds_read_b128 v[140:143], v166 offset:25600
	ds_read_b128 v[144:147], v166 offset:26112
	s_waitcnt lgkmcnt(4)
	s_waitcnt vmcnt(21)
	v_mfma_f32_16x16x32_bf16 v[12:15], v[120:123], v[148:151], v[12:15]
	v_mfma_f32_16x16x32_bf16 v[8:11], v[120:123], v[152:155], v[8:11]
	v_mfma_f32_16x16x32_bf16 v[4:7], v[120:123], v[156:159], v[4:7]
	v_mfma_f32_16x16x32_bf16 v[0:3], v[120:123], v[160:163], v[0:3]
	s_waitcnt vmcnt(20)
	v_mfma_f32_16x16x32_bf16 v[28:31], v[124:127], v[148:151], v[28:31]
	v_mfma_f32_16x16x32_bf16 v[24:27], v[124:127], v[152:155], v[24:27]
	v_mfma_f32_16x16x32_bf16 v[20:23], v[124:127], v[156:159], v[20:23]
	v_mfma_f32_16x16x32_bf16 v[16:19], v[124:127], v[160:163], v[16:19]
	ds_read_b128 v[148:151], v166 offset:28672
	ds_read_b128 v[152:155], v166 offset:29184
	ds_read_b128 v[156:159], v166 offset:29696
	ds_read_b128 v[160:163], v166 offset:30208
	s_waitcnt lgkmcnt(4)
	s_waitcnt vmcnt(19)
	v_mfma_f32_16x16x32_bf16 v[12:15], v[128:131], v[132:135], v[12:15]
	v_mfma_f32_16x16x32_bf16 v[8:11], v[128:131], v[136:139], v[8:11]
	v_mfma_f32_16x16x32_bf16 v[4:7], v[128:131], v[140:143], v[4:7]
	v_mfma_f32_16x16x32_bf16 v[0:3], v[128:131], v[144:147], v[0:3]
	s_waitcnt vmcnt(18)
; #define LAS __attribute__((address_space(3)))
; __device__ __forceinline__ void ssm_a_task(unsigned char* ws, LAS unsigned char* lds, int task, int tid) {
;     ...
;         for (int ks = 0; ks < 16; ++ks) {
;             bf16x8 bfr[4], afr[2];
; #pragma unroll
;             for (int a = 0; a < 2; ++a) afr[a] = *(const bf16x8*)(WA + (size_t)a * 16 * 1024 + (hh * 16 + ks) * 32);
; #pragma unroll
;             for (int c = 0; c < 4; ++c) bfr[c] = *(const LAS bf16x8*)(lds + SS_UB + (((2 * ks + (kk >> 1)) * 64 + c * 16 + rr) * 32 + (kk & 1) * 16));
; #pragma unroll
;             for (int a = 0; a < 2; ++a)
; #pragma unroll
;                 for (int c = 0; c < 4; ++c) acc[a][c] = __builtin_amdgcn_mfma_f32_16x16x32_bf16(afr[a], bfr[c], acc[a][c], 0, 0, 0);
;         }
	v_mfma_f32_16x16x32_bf16 v[28:31], v[168:171], v[132:135], v[28:31]
	v_mfma_f32_16x16x32_bf16 v[24:27], v[168:171], v[136:139], v[24:27]
	v_mfma_f32_16x16x32_bf16 v[20:23], v[168:171], v[140:143], v[20:23]
	v_mfma_f32_16x16x32_bf16 v[16:19], v[168:171], v[144:147], v[16:19]
	ds_read_b128 v[132:135], v166 offset:32768
	ds_read_b128 v[136:139], v166 offset:33280
	ds_read_b128 v[140:143], v166 offset:33792
	ds_read_b128 v[144:147], v166 offset:34304
	s_waitcnt lgkmcnt(4)
	s_waitcnt vmcnt(17)
	v_mfma_f32_16x16x32_bf16 v[12:15], v[172:175], v[148:151], v[12:15]
	v_mfma_f32_16x16x32_bf16 v[8:11], v[172:175], v[152:155], v[8:11]
	v_mfma_f32_16x16x32_bf16 v[4:7], v[172:175], v[156:159], v[4:7]
	v_mfma_f32_16x16x32_bf16 v[0:3], v[172:175], v[160:163], v[0:3]
	s_waitcnt vmcnt(16)
	v_mfma_f32_16x16x32_bf16 v[28:31], v[176:179], v[148:151], v[28:31]
	v_mfma_f32_16x16x32_bf16 v[24:27], v[176:179], v[152:155], v[24:27]
	v_mfma_f32_16x16x32_bf16 v[20:23], v[176:179], v[156:159], v[20:23]
	v_mfma_f32_16x16x32_bf16 v[16:19], v[176:179], v[160:163], v[16:19]
	ds_read_b128 v[148:151], v166 offset:36864
	ds_read_b128 v[152:155], v166 offset:37376
	ds_read_b128 v[156:159], v166 offset:37888
	ds_read_b128 v[160:163], v166 offset:38400
	s_waitcnt lgkmcnt(4)
	s_waitcnt vmcnt(15)
	v_mfma_f32_16x16x32_bf16 v[12:15], v[180:183], v[132:135], v[12:15]
	v_mfma_f32_16x16x32_bf16 v[8:11], v[180:183], v[136:139], v[8:11]
	v_mfma_f32_16x16x32_bf16 v[4:7], v[180:183], v[140:143], v[4:7]
	v_mfma_f32_16x16x32_bf16 v[0:3], v[180:183], v[144:147], v[0:3]
	s_waitcnt vmcnt(14)
	v_mfma_f32_16x16x32_bf16 v[28:31], v[186:189], v[132:135], v[28:31]
	v_mfma_f32_16x16x32_bf16 v[24:27], v[186:189], v[136:139], v[24:27]
	v_mfma_f32_16x16x32_bf16 v[20:23], v[186:189], v[140:143], v[20:23]
	v_mfma_f32_16x16x32_bf16 v[16:19], v[186:189], v[144:147], v[16:19]
	ds_read_b128 v[132:135], v166 offset:40960
	ds_read_b128 v[136:139], v166 offset:41472
	ds_read_b128 v[140:143], v166 offset:41984
	ds_read_b128 v[144:147], v166 offset:42496
	s_waitcnt lgkmcnt(4)
	s_waitcnt vmcnt(13)
	v_mfma_f32_16x16x32_bf16 v[12:15], v[190:193], v[148:151], v[12:15]
	v_mfma_f32_16x16x32_bf16 v[8:11], v[190:193], v[152:155], v[8:11]
	v_mfma_f32_16x16x32_bf16 v[4:7], v[190:193], v[156:159], v[4:7]
	v_mfma_f32_16x16x32_bf16 v[0:3], v[190:193], v[160:163], v[0:3]
	s_waitcnt vmcnt(12)
	v_mfma_f32_16x16x32_bf16 v[28:31], v[194:197], v[148:151], v[28:31]
	v_mfma_f32_16x16x32_bf16 v[24:27], v[194:197], v[152:155], v[24:27]
	v_mfma_f32_16x16x32_bf16 v[20:23], v[194:197], v[156:159], v[20:23]
	v_mfma_f32_16x16x32_bf16 v[16:19], v[194:197], v[160:163], v[16:19]
	ds_read_b128 v[148:151], v166 offset:45056
	ds_read_b128 v[152:155], v166 offset:45568
	ds_read_b128 v[156:159], v166 offset:46080
	ds_read_b128 v[160:163], v166 offset:46592
	s_waitcnt lgkmcnt(4)
	s_waitcnt vmcnt(11)
	v_mfma_f32_16x16x32_bf16 v[12:15], v[198:201], v[132:135], v[12:15]
	v_mfma_f32_16x16x32_bf16 v[8:11], v[198:201], v[136:139], v[8:11]
	v_mfma_f32_16x16x32_bf16 v[4:7], v[198:201], v[140:143], v[4:7]
	v_mfma_f32_16x16x32_bf16 v[0:3], v[198:201], v[144:147], v[0:3]
	s_waitcnt vmcnt(10)
	v_mfma_f32_16x16x32_bf16 v[28:31], v[202:205], v[132:135], v[28:31]
	v_mfma_f32_16x16x32_bf16 v[24:27], v[202:205], v[136:139], v[24:27]
	v_mfma_f32_16x16x32_bf16 v[20:23], v[202:205], v[140:143], v[20:23]
	v_mfma_f32_16x16x32_bf16 v[16:19], v[202:205], v[144:147], v[16:19]
	ds_read_b128 v[132:135], v166 offset:49152
	ds_read_b128 v[136:139], v166 offset:49664
	ds_read_b128 v[140:143], v166 offset:50176
	ds_read_b128 v[144:147], v166 offset:50688
	s_waitcnt lgkmcnt(4)
	s_waitcnt vmcnt(9)
	v_mfma_f32_16x16x32_bf16 v[12:15], v[206:209], v[148:151], v[12:15]
	v_mfma_f32_16x16x32_bf16 v[8:11], v[206:209], v[152:155], v[8:11]
	v_mfma_f32_16x16x32_bf16 v[4:7], v[206:209], v[156:159], v[4:7]
	v_mfma_f32_16x16x32_bf16 v[0:3], v[206:209], v[160:163], v[0:3]
	s_waitcnt vmcnt(8)
	v_mfma_f32_16x16x32_bf16 v[28:31], v[210:213], v[148:151], v[28:31]
	v_mfma_f32_16x16x32_bf16 v[24:27], v[210:213], v[152:155], v[24:27]
	v_mfma_f32_16x16x32_bf16 v[20:23], v[210:213], v[156:159], v[20:23]
	v_mfma_f32_16x16x32_bf16 v[16:19], v[210:213], v[160:163], v[16:19]
	ds_read_b128 v[148:151], v166 offset:53248
	ds_read_b128 v[152:155], v166 offset:53760
	ds_read_b128 v[156:159], v166 offset:54272
	ds_read_b128 v[160:163], v166 offset:54784
	s_waitcnt lgkmcnt(4)
	s_waitcnt vmcnt(7)
	v_mfma_f32_16x16x32_bf16 v[12:15], v[224:227], v[132:135], v[12:15]
	v_mfma_f32_16x16x32_bf16 v[8:11], v[224:227], v[136:139], v[8:11]
	v_mfma_f32_16x16x32_bf16 v[4:7], v[224:227], v[140:143], v[4:7]
	v_mfma_f32_16x16x32_bf16 v[0:3], v[224:227], v[144:147], v[0:3]
	s_waitcnt vmcnt(6)
	v_mfma_f32_16x16x32_bf16 v[28:31], v[228:231], v[132:135], v[28:31]
	v_mfma_f32_16x16x32_bf16 v[24:27], v[228:231], v[136:139], v[24:27]
	v_mfma_f32_16x16x32_bf16 v[20:23], v[228:231], v[140:143], v[20:23]
	v_mfma_f32_16x16x32_bf16 v[16:19], v[228:231], v[144:147], v[16:19]
	ds_read_b128 v[132:135], v166 offset:57344
	ds_read_b128 v[136:139], v166 offset:57856
	ds_read_b128 v[140:143], v166 offset:58368
	ds_read_b128 v[144:147], v166 offset:58880
	s_waitcnt lgkmcnt(4)
	s_waitcnt vmcnt(5)
	v_mfma_f32_16x16x32_bf16 v[12:15], v[232:235], v[148:151], v[12:15]
	v_mfma_f32_16x16x32_bf16 v[8:11], v[232:235], v[152:155], v[8:11]
	v_mfma_f32_16x16x32_bf16 v[4:7], v[232:235], v[156:159], v[4:7]
	v_mfma_f32_16x16x32_bf16 v[0:3], v[232:235], v[160:163], v[0:3]
	s_waitcnt vmcnt(4)
; #define LAS __attribute__((address_space(3)))
; __device__ __forceinline__ void ssm_stage_u(unsigned char* ws, LAS unsigned char* lds, int g, int cb, int hh, int tid) {
;     asm volatile("" : "+v"(tid));
;     const bf16* U = (const bf16*)(ws + AR_U);
;     u32x4 v[8];
; #pragma unroll
;     for (int r = 0; r < 8; ++r) { const int c = r * 512 + tid, jj = c >> 7, col = (c >> 1) & 63, part = c & 1;
;         v[r] = *(const u32x4*)(U + ((size_t)((cb * 64 + col) * 64 + hh * 32 + jj) * 512 + g * 16 + part * 8)); }
; #pragma unroll
;     for (int r = 0; r < 8; ++r) { const int c = r * 512 + tid; *(LAS u32x4*)(lds + SS_UB + c * 16) = v[r]; }
; __device__ __forceinline__ void ssm_a_task(unsigned char* ws, LAS unsigned char* lds, int task, int tid) {
;     ...
;         for (int ks = 0; ks < 16; ++ks) {
;             bf16x8 bfr[4], afr[2];
; #pragma unroll
;             for (int a = 0; a < 2; ++a) afr[a] = *(const bf16x8*)(WA + (size_t)a * 16 * 1024 + (hh * 16 + ks) * 32);
; #pragma unroll
;             for (int c = 0; c < 4; ++c) bfr[c] = *(const LAS bf16x8*)(lds + SS_UB + (((2 * ks + (kk >> 1)) * 64 + c * 16 + rr) * 32 + (kk & 1) * 16));
; #pragma unroll
;             for (int a = 0; a < 2; ++a)
; #pragma unroll
;                 for (int c = 0; c < 4; ++c) acc[a][c] = __builtin_amdgcn_mfma_f32_16x16x32_bf16(afr[a], bfr[c], acc[a][c], 0, 0, 0);
;         }
;         __syncthreads();
;     }
	v_mfma_f32_16x16x32_bf16 v[28:31], v[236:239], v[148:151], v[28:31]
	v_mfma_f32_16x16x32_bf16 v[24:27], v[236:239], v[152:155], v[24:27]
	v_mfma_f32_16x16x32_bf16 v[20:23], v[236:239], v[156:159], v[20:23]
	v_mfma_f32_16x16x32_bf16 v[16:19], v[236:239], v[160:163], v[16:19]
	ds_read_b128 v[148:151], v166 offset:61440
	ds_read_b128 v[152:155], v166 offset:61952
	ds_read_b128 v[156:159], v166 offset:62464
	ds_read_b128 v[160:163], v166 offset:62976
	s_waitcnt lgkmcnt(4)
	s_waitcnt vmcnt(3)
	v_mfma_f32_16x16x32_bf16 v[12:15], v[240:243], v[132:135], v[12:15]
	v_mfma_f32_16x16x32_bf16 v[8:11], v[240:243], v[136:139], v[8:11]
	v_mfma_f32_16x16x32_bf16 v[4:7], v[240:243], v[140:143], v[4:7]
	v_mfma_f32_16x16x32_bf16 v[0:3], v[240:243], v[144:147], v[0:3]
	s_waitcnt vmcnt(2)
	v_mfma_f32_16x16x32_bf16 v[28:31], v[244:247], v[132:135], v[28:31]
	v_mfma_f32_16x16x32_bf16 v[24:27], v[244:247], v[136:139], v[24:27]
	v_mfma_f32_16x16x32_bf16 v[20:23], v[244:247], v[140:143], v[20:23]
	v_mfma_f32_16x16x32_bf16 v[16:19], v[244:247], v[144:147], v[16:19]
	s_waitcnt lgkmcnt(0)
	s_waitcnt vmcnt(1)
	v_mfma_f32_16x16x32_bf16 v[12:15], v[80:83], v[148:151], v[12:15]
	v_mfma_f32_16x16x32_bf16 v[8:11], v[80:83], v[152:155], v[8:11]
	v_mfma_f32_16x16x32_bf16 v[4:7], v[80:83], v[156:159], v[4:7]
	v_mfma_f32_16x16x32_bf16 v[0:3], v[80:83], v[160:163], v[0:3]
	s_waitcnt vmcnt(0)
	v_mfma_f32_16x16x32_bf16 v[28:31], v[84:87], v[148:151], v[28:31]
	v_mfma_f32_16x16x32_bf16 v[24:27], v[84:87], v[152:155], v[24:27]
	v_mfma_f32_16x16x32_bf16 v[20:23], v[84:87], v[156:159], v[20:23]
	v_mfma_f32_16x16x32_bf16 v[16:19], v[84:87], v[160:163], v[16:19]
	s_mov_b32 s12, 0x10000
	v_mov_b32_e32 v72, v44
	s_barrier
	v_lshl_add_u64 v[38:39], v[36:37], 0, v[38:39]
	v_lshlrev_b32_e32 v40, 5, v72
	v_and_b32_e32 v40, 0xfc0, v40
	v_or3_b32 v73, s3, v40, 32
	v_lshlrev_b32_e32 v76, 4, v72
	v_ashrrev_i32_e32 v40, 7, v72
	v_add_u32_e32 v42, 0x200, v72
	v_add_u32_e32 v52, 0x400, v72
	v_add_u32_e32 v54, 0x600, v72
	v_add_u32_e32 v60, 0x800, v72
	v_add_u32_e32 v62, 0xa00, v72
	v_add_u32_e32 v70, 0xc00, v72
	v_add_u32_e32 v72, 0xe00, v72
	v_ashrrev_i32_e32 v42, 7, v42
	v_ashrrev_i32_e32 v52, 7, v52
	v_ashrrev_i32_e32 v54, 7, v54
	v_ashrrev_i32_e32 v60, 7, v60
	v_ashrrev_i32_e32 v62, 7, v62
	v_ashrrev_i32_e32 v70, 7, v70
	v_ashrrev_i32_e32 v72, 7, v72
	v_add_u32_e32 v40, v73, v40
	v_add_u32_e32 v42, v73, v42
	v_add_u32_e32 v52, v73, v52
	v_add_u32_e32 v54, v73, v54
	v_add_u32_e32 v60, v73, v60
	v_add_u32_e32 v62, v73, v62
	v_add_u32_e32 v70, v73, v70
	v_add_u32_e32 v72, v73, v72
	v_and_b32_e32 v184, 16, v76
	v_ashrrev_i32_e32 v41, 31, v40
	v_ashrrev_i32_e32 v43, 31, v42
	v_ashrrev_i32_e32 v53, 31, v52
	v_ashrrev_i32_e32 v55, 31, v54
	v_ashrrev_i32_e32 v61, 31, v60
	v_ashrrev_i32_e32 v63, 31, v62
	v_ashrrev_i32_e32 v71, 31, v70
	v_ashrrev_i32_e32 v73, 31, v72
	v_lshl_add_u64 v[68:69], s[34:35], 0, v[184:185]
	v_lshlrev_b64 v[40:41], 10, v[40:41]
	v_lshlrev_b64 v[42:43], 10, v[42:43]
	v_lshlrev_b64 v[52:53], 10, v[52:53]
	v_lshlrev_b64 v[54:55], 10, v[54:55]
	v_lshlrev_b64 v[60:61], 10, v[60:61]
	v_lshlrev_b64 v[62:63], 10, v[62:63]
	v_lshlrev_b64 v[70:71], 10, v[70:71]
	v_lshlrev_b64 v[72:73], 10, v[72:73]
	v_lshl_add_u64 v[40:41], v[68:69], 0, v[40:41]
	v_lshl_add_u64 v[48:49], v[68:69], 0, v[42:43]
	v_lshl_add_u64 v[52:53], v[68:69], 0, v[52:53]
	v_lshl_add_u64 v[56:57], v[68:69], 0, v[54:55]
	v_lshl_add_u64 v[60:61], v[68:69], 0, v[60:61]
	v_lshl_add_u64 v[64:65], v[68:69], 0, v[62:63]
	v_lshl_add_u64 v[70:71], v[68:69], 0, v[70:71]
	v_lshl_add_u64 v[72:73], v[68:69], 0, v[72:73]
	global_load_dwordx4 v[40:43], v[40:41], off
	s_nop 0
	global_load_dwordx4 v[48:51], v[48:49], off
	s_nop 0
	global_load_dwordx4 v[52:55], v[52:53], off
	s_nop 0
	global_load_dwordx4 v[56:59], v[56:57], off
	s_nop 0
	global_load_dwordx4 v[60:63], v[60:61], off
	s_nop 0
	global_load_dwordx4 v[64:67], v[64:65], off
	s_nop 0
	global_load_dwordx4 v[68:71], v[70:71], off
	s_nop 0
	global_load_dwordx4 v[72:75], v[72:73], off
	v_add_u32_e32 v76, 0, v76
	v_add_u32_e32 v76, 0x10000, v76
	s_mov_b32 s3, 0
	v_add_co_u32_e32 v164, vcc, 0xffff8000, v38
	s_nop 1
	v_addc_co_u32_e32 v165, vcc, -1, v39, vcc
	global_load_dwordx4 v[80:83], v[38:39], off offset:-192
	global_load_dwordx4 v[84:87], v[164:165], off offset:-192
	global_load_dwordx4 v[88:91], v[38:39], off offset:-128
	global_load_dwordx4 v[92:95], v[164:165], off offset:-128
	global_load_dwordx4 v[96:99], v[38:39], off offset:-64
	global_load_dwordx4 v[100:103], v[164:165], off offset:-64
	global_load_dwordx4 v[104:107], v[38:39], off offset:0
	global_load_dwordx4 v[108:111], v[164:165], off offset:0
	global_load_dwordx4 v[112:115], v[38:39], off offset:64
	global_load_dwordx4 v[116:119], v[164:165], off offset:64
	global_load_dwordx4 v[120:123], v[38:39], off offset:128
	global_load_dwordx4 v[124:127], v[164:165], off offset:128
	global_load_dwordx4 v[128:131], v[38:39], off offset:192
	global_load_dwordx4 v[168:171], v[164:165], off offset:192
	global_load_dwordx4 v[172:175], v[38:39], off offset:256
	global_load_dwordx4 v[176:179], v[164:165], off offset:256
	global_load_dwordx4 v[180:183], v[38:39], off offset:320
	global_load_dwordx4 v[186:189], v[164:165], off offset:320
	global_load_dwordx4 v[190:193], v[38:39], off offset:384
	global_load_dwordx4 v[194:197], v[164:165], off offset:384
	global_load_dwordx4 v[198:201], v[38:39], off offset:448
	global_load_dwordx4 v[202:205], v[164:165], off offset:448
	global_load_dwordx4 v[206:209], v[38:39], off offset:512
	global_load_dwordx4 v[210:213], v[164:165], off offset:512
	global_load_dwordx4 v[224:227], v[38:39], off offset:576
	global_load_dwordx4 v[228:231], v[164:165], off offset:576
	global_load_dwordx4 v[232:235], v[38:39], off offset:640
	global_load_dwordx4 v[236:239], v[164:165], off offset:640
	global_load_dwordx4 v[240:243], v[38:39], off offset:704
	global_load_dwordx4 v[244:247], v[164:165], off offset:704
	s_waitcnt vmcnt(37)
	ds_write_b128 v76, v[40:43]
	s_waitcnt vmcnt(36)
	ds_write_b128 v76, v[48:51] offset:8192
	s_waitcnt vmcnt(35)
	ds_write_b128 v76, v[52:55] offset:16384
	s_waitcnt vmcnt(34)
	ds_write_b128 v76, v[56:59] offset:24576
	s_waitcnt vmcnt(33)
	ds_write_b128 v76, v[60:63] offset:32768
	s_waitcnt vmcnt(32)
	ds_write_b128 v76, v[64:67] offset:40960
	s_waitcnt vmcnt(31)
	ds_write_b128 v76, v[68:71] offset:49152
	s_waitcnt vmcnt(30)
	ds_write_b128 v76, v[72:75] offset:57344
	s_waitcnt lgkmcnt(0)
	s_barrier
; #define LAS __attribute__((address_space(3)))
; __device__ __forceinline__ void ssm_a_task(unsigned char* ws, LAS unsigned char* lds, int task, int tid) {
;     ...
;         for (int ks = 0; ks < 16; ++ks) {
;             bf16x8 bfr[4], afr[2];
; #pragma unroll
;             for (int a = 0; a < 2; ++a) afr[a] = *(const bf16x8*)(WA + (size_t)a * 16 * 1024 + (hh * 16 + ks) * 32);
; #pragma unroll
;             for (int c = 0; c < 4; ++c) bfr[c] = *(const LAS bf16x8*)(lds + SS_UB + (((2 * ks + (kk >> 1)) * 64 + c * 16 + rr) * 32 + (kk & 1) * 16));
; #pragma unroll
;             for (int a = 0; a < 2; ++a)
; #pragma unroll
;                 for (int c = 0; c < 4; ++c) acc[a][c] = __builtin_amdgcn_mfma_f32_16x16x32_bf16(afr[a], bfr[c], acc[a][c], 0, 0, 0);
;         }
.LBB0_606:
	v_add_u32_e32 v166, 0x10000, v47
	ds_read_b128 v[132:135], v166 offset:0
	ds_read_b128 v[136:139], v166 offset:512
	ds_read_b128 v[140:143], v166 offset:1024
	ds_read_b128 v[144:147], v166 offset:1536
	ds_read_b128 v[148:151], v166 offset:4096
	ds_read_b128 v[152:155], v166 offset:4608
	ds_read_b128 v[156:159], v166 offset:5120
	ds_read_b128 v[160:163], v166 offset:5632
	s_waitcnt lgkmcnt(4)
	s_waitcnt vmcnt(29)
	v_mfma_f32_16x16x32_bf16 v[12:15], v[80:83], v[132:135], v[12:15]
	v_mfma_f32_16x16x32_bf16 v[8:11], v[80:83], v[136:139], v[8:11]
	v_mfma_f32_16x16x32_bf16 v[4:7], v[80:83], v[140:143], v[4:7]
	v_mfma_f32_16x16x32_bf16 v[0:3], v[80:83], v[144:147], v[0:3]
	s_waitcnt vmcnt(28)
	v_mfma_f32_16x16x32_bf16 v[28:31], v[84:87], v[132:135], v[28:31]
	v_mfma_f32_16x16x32_bf16 v[24:27], v[84:87], v[136:139], v[24:27]
	v_mfma_f32_16x16x32_bf16 v[20:23], v[84:87], v[140:143], v[20:23]
	v_mfma_f32_16x16x32_bf16 v[16:19], v[84:87], v[144:147], v[16:19]
	global_load_dwordx4 v[80:83], v[38:39], off offset:768
	global_load_dwordx4 v[84:87], v[164:165], off offset:768
	ds_read_b128 v[132:135], v166 offset:8192
	ds_read_b128 v[136:139], v166 offset:8704
	ds_read_b128 v[140:143], v166 offset:9216
	ds_read_b128 v[144:147], v166 offset:9728
	s_waitcnt lgkmcnt(4)
	s_waitcnt vmcnt(29)
	v_mfma_f32_16x16x32_bf16 v[12:15], v[88:91], v[148:151], v[12:15]
	v_mfma_f32_16x16x32_bf16 v[8:11], v[88:91], v[152:155], v[8:11]
	v_mfma_f32_16x16x32_bf16 v[4:7], v[88:91], v[156:159], v[4:7]
	v_mfma_f32_16x16x32_bf16 v[0:3], v[88:91], v[160:163], v[0:3]
	s_waitcnt vmcnt(28)
	v_mfma_f32_16x16x32_bf16 v[28:31], v[92:95], v[148:151], v[28:31]
	v_mfma_f32_16x16x32_bf16 v[24:27], v[92:95], v[152:155], v[24:27]
	v_mfma_f32_16x16x32_bf16 v[20:23], v[92:95], v[156:159], v[20:23]
	v_mfma_f32_16x16x32_bf16 v[16:19], v[92:95], v[160:163], v[16:19]
	ds_read_b128 v[148:151], v166 offset:12288
	ds_read_b128 v[152:155], v166 offset:12800
	ds_read_b128 v[156:159], v166 offset:13312
	ds_read_b128 v[160:163], v166 offset:13824
	s_waitcnt lgkmcnt(4)
	s_waitcnt vmcnt(27)
	v_mfma_f32_16x16x32_bf16 v[12:15], v[96:99], v[132:135], v[12:15]
	v_mfma_f32_16x16x32_bf16 v[8:11], v[96:99], v[136:139], v[8:11]
	v_mfma_f32_16x16x32_bf16 v[4:7], v[96:99], v[140:143], v[4:7]
	v_mfma_f32_16x16x32_bf16 v[0:3], v[96:99], v[144:147], v[0:3]
	s_waitcnt vmcnt(26)
	v_mfma_f32_16x16x32_bf16 v[28:31], v[100:103], v[132:135], v[28:31]
	v_mfma_f32_16x16x32_bf16 v[24:27], v[100:103], v[136:139], v[24:27]
	v_mfma_f32_16x16x32_bf16 v[20:23], v[100:103], v[140:143], v[20:23]
	v_mfma_f32_16x16x32_bf16 v[16:19], v[100:103], v[144:147], v[16:19]
	ds_read_b128 v[132:135], v166 offset:16384
	ds_read_b128 v[136:139], v166 offset:16896
	ds_read_b128 v[140:143], v166 offset:17408
	ds_read_b128 v[144:147], v166 offset:17920
	s_waitcnt lgkmcnt(4)
	s_waitcnt vmcnt(25)
	v_mfma_f32_16x16x32_bf16 v[12:15], v[104:107], v[148:151], v[12:15]
	v_mfma_f32_16x16x32_bf16 v[8:11], v[104:107], v[152:155], v[8:11]
	v_mfma_f32_16x16x32_bf16 v[4:7], v[104:107], v[156:159], v[4:7]
	v_mfma_f32_16x16x32_bf16 v[0:3], v[104:107], v[160:163], v[0:3]
	s_waitcnt vmcnt(24)
	v_mfma_f32_16x16x32_bf16 v[28:31], v[108:111], v[148:151], v[28:31]
	v_mfma_f32_16x16x32_bf16 v[24:27], v[108:111], v[152:155], v[24:27]
	v_mfma_f32_16x16x32_bf16 v[20:23], v[108:111], v[156:159], v[20:23]
	v_mfma_f32_16x16x32_bf16 v[16:19], v[108:111], v[160:163], v[16:19]
	ds_read_b128 v[148:151], v166 offset:20480
	ds_read_b128 v[152:155], v166 offset:20992
	ds_read_b128 v[156:159], v166 offset:21504
	ds_read_b128 v[160:163], v166 offset:22016
	s_waitcnt lgkmcnt(4)
	s_waitcnt vmcnt(23)
	v_mfma_f32_16x16x32_bf16 v[12:15], v[112:115], v[132:135], v[12:15]
	v_mfma_f32_16x16x32_bf16 v[8:11], v[112:115], v[136:139], v[8:11]
	v_mfma_f32_16x16x32_bf16 v[4:7], v[112:115], v[140:143], v[4:7]
	v_mfma_f32_16x16x32_bf16 v[0:3], v[112:115], v[144:147], v[0:3]
	s_waitcnt vmcnt(22)
	v_mfma_f32_16x16x32_bf16 v[28:31], v[116:119], v[132:135], v[28:31]
	v_mfma_f32_16x16x32_bf16 v[24:27], v[116:119], v[136:139], v[24:27]
	v_mfma_f32_16x16x32_bf16 v[20:23], v[116:119], v[140:143], v[20:23]
	v_mfma_f32_16x16x32_bf16 v[16:19], v[116:119], v[144:147], v[16:19]
	ds_read_b128 v[132:135], v166 offset:24576
	ds_read_b128 v[136:139], v166 offset:25088
	ds_read_b128 v[140:143], v166 offset:25600
	ds_read_b128 v[144:147], v166 offset:26112
	s_waitcnt lgkmcnt(4)
	s_waitcnt vmcnt(21)
	v_mfma_f32_16x16x32_bf16 v[12:15], v[120:123], v[148:151], v[12:15]
	v_mfma_f32_16x16x32_bf16 v[8:11], v[120:123], v[152:155], v[8:11]
	v_mfma_f32_16x16x32_bf16 v[4:7], v[120:123], v[156:159], v[4:7]
	v_mfma_f32_16x16x32_bf16 v[0:3], v[120:123], v[160:163], v[0:3]
	s_waitcnt vmcnt(20)
	v_mfma_f32_16x16x32_bf16 v[28:31], v[124:127], v[148:151], v[28:31]
	v_mfma_f32_16x16x32_bf16 v[24:27], v[124:127], v[152:155], v[24:27]
	v_mfma_f32_16x16x32_bf16 v[20:23], v[124:127], v[156:159], v[20:23]
	v_mfma_f32_16x16x32_bf16 v[16:19], v[124:127], v[160:163], v[16:19]
	ds_read_b128 v[148:151], v166 offset:28672
	ds_read_b128 v[152:155], v166 offset:29184
	ds_read_b128 v[156:159], v166 offset:29696
	ds_read_b128 v[160:163], v166 offset:30208
	s_waitcnt lgkmcnt(4)
	s_waitcnt vmcnt(19)
	v_mfma_f32_16x16x32_bf16 v[12:15], v[128:131], v[132:135], v[12:15]
	v_mfma_f32_16x16x32_bf16 v[8:11], v[128:131], v[136:139], v[8:11]
	v_mfma_f32_16x16x32_bf16 v[4:7], v[128:131], v[140:143], v[4:7]
	v_mfma_f32_16x16x32_bf16 v[0:3], v[128:131], v[144:147], v[0:3]
	s_waitcnt vmcnt(18)
; #define LAS __attribute__((address_space(3)))
; __device__ __forceinline__ void ssm_a_task(unsigned char* ws, LAS unsigned char* lds, int task, int tid) {
;     ...
;         for (int ks = 0; ks < 16; ++ks) {
;             bf16x8 bfr[4], afr[2];
; #pragma unroll
;             for (int a = 0; a < 2; ++a) afr[a] = *(const bf16x8*)(WA + (size_t)a * 16 * 1024 + (hh * 16 + ks) * 32);
; #pragma unroll
;             for (int c = 0; c < 4; ++c) bfr[c] = *(const LAS bf16x8*)(lds + SS_UB + (((2 * ks + (kk >> 1)) * 64 + c * 16 + rr) * 32 + (kk & 1) * 16));
; #pragma unroll
;             for (int a = 0; a < 2; ++a)
; #pragma unroll
;                 for (int c = 0; c < 4; ++c) acc[a][c] = __builtin_amdgcn_mfma_f32_16x16x32_bf16(afr[a], bfr[c], acc[a][c], 0, 0, 0);
;         }
	v_mfma_f32_16x16x32_bf16 v[28:31], v[168:171], v[132:135], v[28:31]
	v_mfma_f32_16x16x32_bf16 v[24:27], v[168:171], v[136:139], v[24:27]
	v_mfma_f32_16x16x32_bf16 v[20:23], v[168:171], v[140:143], v[20:23]
	v_mfma_f32_16x16x32_bf16 v[16:19], v[168:171], v[144:147], v[16:19]
	ds_read_b128 v[132:135], v166 offset:32768
	ds_read_b128 v[136:139], v166 offset:33280
	ds_read_b128 v[140:143], v166 offset:33792
	ds_read_b128 v[144:147], v166 offset:34304
	s_waitcnt lgkmcnt(4)
	s_waitcnt vmcnt(17)
	v_mfma_f32_16x16x32_bf16 v[12:15], v[172:175], v[148:151], v[12:15]
	v_mfma_f32_16x16x32_bf16 v[8:11], v[172:175], v[152:155], v[8:11]
	v_mfma_f32_16x16x32_bf16 v[4:7], v[172:175], v[156:159], v[4:7]
	v_mfma_f32_16x16x32_bf16 v[0:3], v[172:175], v[160:163], v[0:3]
	s_waitcnt vmcnt(16)
	v_mfma_f32_16x16x32_bf16 v[28:31], v[176:179], v[148:151], v[28:31]
	v_mfma_f32_16x16x32_bf16 v[24:27], v[176:179], v[152:155], v[24:27]
	v_mfma_f32_16x16x32_bf16 v[20:23], v[176:179], v[156:159], v[20:23]
	v_mfma_f32_16x16x32_bf16 v[16:19], v[176:179], v[160:163], v[16:19]
	ds_read_b128 v[148:151], v166 offset:36864
	ds_read_b128 v[152:155], v166 offset:37376
	ds_read_b128 v[156:159], v166 offset:37888
	ds_read_b128 v[160:163], v166 offset:38400
	s_waitcnt lgkmcnt(4)
	s_waitcnt vmcnt(15)
	v_mfma_f32_16x16x32_bf16 v[12:15], v[180:183], v[132:135], v[12:15]
	v_mfma_f32_16x16x32_bf16 v[8:11], v[180:183], v[136:139], v[8:11]
	v_mfma_f32_16x16x32_bf16 v[4:7], v[180:183], v[140:143], v[4:7]
	v_mfma_f32_16x16x32_bf16 v[0:3], v[180:183], v[144:147], v[0:3]
	s_waitcnt vmcnt(14)
	v_mfma_f32_16x16x32_bf16 v[28:31], v[186:189], v[132:135], v[28:31]
	v_mfma_f32_16x16x32_bf16 v[24:27], v[186:189], v[136:139], v[24:27]
	v_mfma_f32_16x16x32_bf16 v[20:23], v[186:189], v[140:143], v[20:23]
	v_mfma_f32_16x16x32_bf16 v[16:19], v[186:189], v[144:147], v[16:19]
	ds_read_b128 v[132:135], v166 offset:40960
	ds_read_b128 v[136:139], v166 offset:41472
	ds_read_b128 v[140:143], v166 offset:41984
	ds_read_b128 v[144:147], v166 offset:42496
	s_waitcnt lgkmcnt(4)
	s_waitcnt vmcnt(13)
	v_mfma_f32_16x16x32_bf16 v[12:15], v[190:193], v[148:151], v[12:15]
	v_mfma_f32_16x16x32_bf16 v[8:11], v[190:193], v[152:155], v[8:11]
	v_mfma_f32_16x16x32_bf16 v[4:7], v[190:193], v[156:159], v[4:7]
	v_mfma_f32_16x16x32_bf16 v[0:3], v[190:193], v[160:163], v[0:3]
	s_waitcnt vmcnt(12)
	v_mfma_f32_16x16x32_bf16 v[28:31], v[194:197], v[148:151], v[28:31]
	v_mfma_f32_16x16x32_bf16 v[24:27], v[194:197], v[152:155], v[24:27]
	v_mfma_f32_16x16x32_bf16 v[20:23], v[194:197], v[156:159], v[20:23]
	v_mfma_f32_16x16x32_bf16 v[16:19], v[194:197], v[160:163], v[16:19]
	ds_read_b128 v[148:151], v166 offset:45056
	ds_read_b128 v[152:155], v166 offset:45568
	ds_read_b128 v[156:159], v166 offset:46080
	ds_read_b128 v[160:163], v166 offset:46592
	s_waitcnt lgkmcnt(4)
	s_waitcnt vmcnt(11)
	v_mfma_f32_16x16x32_bf16 v[12:15], v[198:201], v[132:135], v[12:15]
	v_mfma_f32_16x16x32_bf16 v[8:11], v[198:201], v[136:139], v[8:11]
	v_mfma_f32_16x16x32_bf16 v[4:7], v[198:201], v[140:143], v[4:7]
	v_mfma_f32_16x16x32_bf16 v[0:3], v[198:201], v[144:147], v[0:3]
	s_waitcnt vmcnt(10)
	v_mfma_f32_16x16x32_bf16 v[28:31], v[202:205], v[132:135], v[28:31]
	v_mfma_f32_16x16x32_bf16 v[24:27], v[202:205], v[136:139], v[24:27]
	v_mfma_f32_16x16x32_bf16 v[20:23], v[202:205], v[140:143], v[20:23]
	v_mfma_f32_16x16x32_bf16 v[16:19], v[202:205], v[144:147], v[16:19]
	ds_read_b128 v[132:135], v166 offset:49152
	ds_read_b128 v[136:139], v166 offset:49664
	ds_read_b128 v[140:143], v166 offset:50176
	ds_read_b128 v[144:147], v166 offset:50688
	s_waitcnt lgkmcnt(4)
	s_waitcnt vmcnt(9)
	v_mfma_f32_16x16x32_bf16 v[12:15], v[206:209], v[148:151], v[12:15]
	v_mfma_f32_16x16x32_bf16 v[8:11], v[206:209], v[152:155], v[8:11]
	v_mfma_f32_16x16x32_bf16 v[4:7], v[206:209], v[156:159], v[4:7]
	v_mfma_f32_16x16x32_bf16 v[0:3], v[206:209], v[160:163], v[0:3]
	s_waitcnt vmcnt(8)
; #define LAS __attribute__((address_space(3)))
; __device__ __forceinline__ void ssm_a_task(unsigned char* ws, LAS unsigned char* lds, int task, int tid) {
;     ...
;             for (int c = 0; c < 4; ++c) bfr[c] = *(const LAS bf16x8*)(lds + SS_UB + (((2 * ks + (kk >> 1)) * 64 + c * 16 + rr) * 32 + (kk & 1) * 16));
; #pragma unroll
;             for (int a = 0; a < 2; ++a)
; #pragma unroll
;                 for (int c = 0; c < 4; ++c) acc[a][c] = __builtin_amdgcn_mfma_f32_16x16x32_bf16(afr[a], bfr[c], acc[a][c], 0, 0, 0);
;         }
;         __syncthreads();
;     }
;     float* S = (float*)(ws + AR_S);
; #pragma unroll
;     for (int a = 0; a < 2; ++a)
; #pragma unroll
;         for (int c = 0; c < 4; ++c) { const int col = cb * 64 + c * 16 + rr; *(f32x4*)(S + ((size_t)(col * NG + g) * 256 + wid * 32 + a * 16 + 4 * kk)) = acc[a][c]; }
	v_mfma_f32_16x16x32_bf16 v[28:31], v[210:213], v[148:151], v[28:31]
	v_mfma_f32_16x16x32_bf16 v[24:27], v[210:213], v[152:155], v[24:27]
	v_mfma_f32_16x16x32_bf16 v[20:23], v[210:213], v[156:159], v[20:23]
	v_mfma_f32_16x16x32_bf16 v[16:19], v[210:213], v[160:163], v[16:19]
	ds_read_b128 v[148:151], v166 offset:53248
	ds_read_b128 v[152:155], v166 offset:53760
	ds_read_b128 v[156:159], v166 offset:54272
	ds_read_b128 v[160:163], v166 offset:54784
	s_waitcnt lgkmcnt(4)
	s_waitcnt vmcnt(7)
	v_mfma_f32_16x16x32_bf16 v[12:15], v[224:227], v[132:135], v[12:15]
	v_mfma_f32_16x16x32_bf16 v[8:11], v[224:227], v[136:139], v[8:11]
	v_mfma_f32_16x16x32_bf16 v[4:7], v[224:227], v[140:143], v[4:7]
	v_mfma_f32_16x16x32_bf16 v[0:3], v[224:227], v[144:147], v[0:3]
	s_waitcnt vmcnt(6)
	v_mfma_f32_16x16x32_bf16 v[28:31], v[228:231], v[132:135], v[28:31]
	v_mfma_f32_16x16x32_bf16 v[24:27], v[228:231], v[136:139], v[24:27]
	v_mfma_f32_16x16x32_bf16 v[20:23], v[228:231], v[140:143], v[20:23]
	v_mfma_f32_16x16x32_bf16 v[16:19], v[228:231], v[144:147], v[16:19]
	ds_read_b128 v[132:135], v166 offset:57344
	ds_read_b128 v[136:139], v166 offset:57856
	ds_read_b128 v[140:143], v166 offset:58368
	ds_read_b128 v[144:147], v166 offset:58880
	s_waitcnt lgkmcnt(4)
	s_waitcnt vmcnt(5)
	v_mfma_f32_16x16x32_bf16 v[12:15], v[232:235], v[148:151], v[12:15]
	v_mfma_f32_16x16x32_bf16 v[8:11], v[232:235], v[152:155], v[8:11]
	v_mfma_f32_16x16x32_bf16 v[4:7], v[232:235], v[156:159], v[4:7]
	v_mfma_f32_16x16x32_bf16 v[0:3], v[232:235], v[160:163], v[0:3]
	s_waitcnt vmcnt(4)
	v_mfma_f32_16x16x32_bf16 v[28:31], v[236:239], v[148:151], v[28:31]
	v_mfma_f32_16x16x32_bf16 v[24:27], v[236:239], v[152:155], v[24:27]
	v_mfma_f32_16x16x32_bf16 v[20:23], v[236:239], v[156:159], v[20:23]
	v_mfma_f32_16x16x32_bf16 v[16:19], v[236:239], v[160:163], v[16:19]
	ds_read_b128 v[148:151], v166 offset:61440
	ds_read_b128 v[152:155], v166 offset:61952
	ds_read_b128 v[156:159], v166 offset:62464
	ds_read_b128 v[160:163], v166 offset:62976
	s_waitcnt lgkmcnt(4)
	s_waitcnt vmcnt(3)
	v_mfma_f32_16x16x32_bf16 v[12:15], v[240:243], v[132:135], v[12:15]
	v_mfma_f32_16x16x32_bf16 v[8:11], v[240:243], v[136:139], v[8:11]
	v_mfma_f32_16x16x32_bf16 v[4:7], v[240:243], v[140:143], v[4:7]
	v_mfma_f32_16x16x32_bf16 v[0:3], v[240:243], v[144:147], v[0:3]
	s_waitcnt vmcnt(2)
	v_mfma_f32_16x16x32_bf16 v[28:31], v[244:247], v[132:135], v[28:31]
	v_mfma_f32_16x16x32_bf16 v[24:27], v[244:247], v[136:139], v[24:27]
	v_mfma_f32_16x16x32_bf16 v[20:23], v[244:247], v[140:143], v[20:23]
	v_mfma_f32_16x16x32_bf16 v[16:19], v[244:247], v[144:147], v[16:19]
	s_waitcnt lgkmcnt(0)
	s_waitcnt vmcnt(1)
	v_mfma_f32_16x16x32_bf16 v[12:15], v[80:83], v[148:151], v[12:15]
	v_mfma_f32_16x16x32_bf16 v[8:11], v[80:83], v[152:155], v[8:11]
	v_mfma_f32_16x16x32_bf16 v[4:7], v[80:83], v[156:159], v[4:7]
	v_mfma_f32_16x16x32_bf16 v[0:3], v[80:83], v[160:163], v[0:3]
	s_waitcnt vmcnt(0)
	v_mfma_f32_16x16x32_bf16 v[28:31], v[84:87], v[148:151], v[28:31]
	v_mfma_f32_16x16x32_bf16 v[24:27], v[84:87], v[152:155], v[24:27]
	v_mfma_f32_16x16x32_bf16 v[20:23], v[84:87], v[156:159], v[20:23]
	v_mfma_f32_16x16x32_bf16 v[16:19], v[84:87], v[160:163], v[16:19]
	s_mov_b32 s3, 0x10000
	v_lshl_or_b32 v38, s17, 11, v45
	v_add_u32_e32 v38, s16, v38
	v_ashrrev_i32_e32 v39, 31, v38
	v_lshlrev_b64 v[40:41], 10, v[38:39]
	v_lshl_add_u64 v[40:41], v[32:33], 0, v[40:41]
	s_barrier
	global_store_dwordx4 v[40:41], v[28:31], off
	s_add_i32 s54, s54, s76
	s_cmpk_gt_i32 s54, 0xff
	v_add_u32_e32 v28, 0x200, v38
	v_ashrrev_i32_e32 v29, 31, v28
	v_lshlrev_b64 v[28:29], 10, v[28:29]
	v_lshl_add_u64 v[28:29], v[32:33], 0, v[28:29]
	global_store_dwordx4 v[28:29], v[24:27], off
	s_nop 1
	v_add_u32_e32 v24, 0x400, v38
	v_ashrrev_i32_e32 v25, 31, v24
	v_lshlrev_b64 v[24:25], 10, v[24:25]
	v_lshl_add_u64 v[24:25], v[32:33], 0, v[24:25]
	global_store_dwordx4 v[24:25], v[20:23], off
	s_nop 1
	v_add_u32_e32 v20, 0x600, v38
	v_ashrrev_i32_e32 v21, 31, v20
	v_lshlrev_b64 v[20:21], 10, v[20:21]
	v_lshl_add_u64 v[20:21], v[32:33], 0, v[20:21]
	global_store_dwordx4 v[20:21], v[16:19], off
	global_store_dwordx4 v[40:41], v[12:15], off offset:64
	global_store_dwordx4 v[28:29], v[8:11], off offset:64
	global_store_dwordx4 v[24:25], v[4:7], off offset:64
	global_store_dwordx4 v[20:21], v[0:3], off offset:64
	s_cbranch_scc0 .LBB0_603
